# all remaining workspace-pointer kernarg s_loads (unit-loop headers, epilogue starts) replaced by the copy cached in s[100:101]
# speedup vs baseline: 1.0004x; 1.0004x over previous
.Lchain_nowb:
	s_waitcnt vmcnt(0) lgkmcnt(0)
	s_waitcnt vmcnt(0)
	s_mov_b64 s[6:7], s[100:101]
	s_lshl_b32 s8, s96, 6
	s_ashr_i32 s9, s8, 31
	s_lshl_b64 s[8:9], s[8:9], 2
	s_waitcnt lgkmcnt(0)
	s_add_u32 s6, s6, s8
	s_addc_u32 s7, s7, s9
	global_store_dword v151, v147, s[6:7] sc1

.LBB0_702:
	s_add_i32 s10, s63, 0xffffffb8
	s_ashr_i32 s63, s10, 5
	s_lshl_b32 s26, 1, s63
	s_and_b32 s6, s26, s70
	s_cmp_lg_u32 s6, 0
	s_cbranch_scc1 .LBB0_714
	s_and_b64 vcc, exec, s[4:5]
	s_cbranch_vccnz .LBB0_713
	s_mov_b64 s[6:7], s[0:1]
	s_mov_b64 s[6:7], s[100:101]
	s_lshl_b32 s8, s51, 2
	s_waitcnt lgkmcnt(0)
	s_add_u32 s6, s6, s8
	s_addc_u32 s7, s7, 0
	s_add_u32 s6, s6, 0x20000
	s_addc_u32 s7, s7, 0
	s_mov_b32 s27, 0x3fffff

.Lgbv_join:
	v_lshlrev_b32_e32 v8, 16, v84
	v_and_b32_e32 v9, 0xffff0000, v84
	s_nop 0
	v_and_b32_e32 v11, 0xffff0000, v80
	s_waitcnt lgkmcnt(0)
	v_pk_mul_f32 v[0:1], v[0:1], v[4:5]
	v_pk_mul_f32 v[2:3], v[2:3], v[6:7]
	ds_write_b128 v16, v[0:3] offset:64
	ds_read_b128 v[0:3], v23 offset:96
	v_pk_mul_f32 v[4:5], v[12:13], v[20:21] op_sel_hi:[1,0]
	v_pk_mul_f32 v[6:7], v[14:15], v[20:21] op_sel_hi:[1,0]
	s_waitcnt lgkmcnt(0)
	v_pk_mul_f32 v[0:1], v[0:1], v[4:5]
	v_pk_mul_f32 v[2:3], v[2:3], v[6:7]
	ds_write_b128 v16, v[0:3] offset:96
	v_lshlrev_b32_e32 v0, 2, v203
	v_mul_lo_u32 v1, v202, s69
	s_waitcnt lgkmcnt(0)
	s_barrier
	v_add3_u32 v10, 0, v0, v1
	ds_read_b128 v[0:3], v10
	ds_read_b128 v[4:7], v10 offset:16
	s_mov_b64 s[6:7], s[100:101]
	s_waitcnt lgkmcnt(0)
	v_pk_mul_f32 v[0:1], v[0:1], v[8:9]
	v_lshlrev_b32_e32 v8, 16, v85
	v_and_b32_e32 v9, 0xffff0000, v85
	v_pk_mul_f32 v[2:3], v[2:3], v[8:9]
	v_cvt_pk_bf16_f32 v0, v0, v1
	v_cvt_pk_bf16_f32 v1, v2, v3
	v_lshlrev_b32_e32 v2, 16, v86
	v_and_b32_e32 v3, 0xffff0000, v86
	v_pk_mul_f32 v[2:3], v[4:5], v[2:3]
	v_lshlrev_b32_e32 v4, 16, v87
	v_and_b32_e32 v5, 0xffff0000, v87
	v_pk_mul_f32 v[4:5], v[6:7], v[4:5]
	v_cvt_pk_bf16_f32 v2, v2, v3
	v_cvt_pk_bf16_f32 v3, v4, v5
	v_lshlrev_b64 v[4:5], 11, v[204:205]
	v_lshl_add_u64 v[4:5], s[6:7], 0, v[4:5]
	v_lshl_add_u64 v[4:5], v[4:5], 0, s[42:43]
	v_lshl_add_u64 v[4:5], v[4:5], 0, v[200:201]
	v_add_co_u32_e32 v4, vcc, s45, v4
	s_mov_b64 s[6:7], s[0:1]
	s_nop 0
	v_addc_co_u32_e32 v5, vcc, 0, v5, vcc
	global_store_dwordx4 v[4:5], v[0:3], off offset:1024
	ds_read_b128 v[0:3], v10 offset:16896
	ds_read_b128 v[4:7], v10 offset:16912
	v_lshlrev_b32_e32 v10, 16, v80
	s_mov_b64 s[6:7], s[100:101]
	s_waitcnt lgkmcnt(0)
	v_pk_mul_f32 v[0:1], v[0:1], v[10:11]
	v_lshlrev_b32_e32 v10, 16, v81
	v_and_b32_e32 v11, 0xffff0000, v81
	v_pk_mul_f32 v[2:3], v[2:3], v[10:11]
	v_cvt_pk_bf16_f32 v0, v0, v1
	v_cvt_pk_bf16_f32 v1, v2, v3
	v_lshlrev_b32_e32 v2, 16, v82
	v_and_b32_e32 v3, 0xffff0000, v82
	v_add_u32_e32 v8, 32, v202
	v_pk_mul_f32 v[2:3], v[4:5], v[2:3]
	v_lshlrev_b32_e32 v4, 16, v83
	v_and_b32_e32 v5, 0xffff0000, v83
	v_pk_mul_f32 v[4:5], v[6:7], v[4:5]
	v_ashrrev_i32_e32 v9, 31, v8
	v_cvt_pk_bf16_f32 v2, v2, v3
	v_cvt_pk_bf16_f32 v3, v4, v5
	v_lshl_add_u64 v[4:5], v[8:9], 0, s[10:11]
	v_lshlrev_b64 v[4:5], 11, v[4:5]
	v_lshl_add_u64 v[4:5], s[6:7], 0, v[4:5]
	v_lshl_add_u64 v[4:5], v[4:5], 0, s[42:43]
	v_lshl_add_u64 v[4:5], v[4:5], 0, v[200:201]
	v_add_co_u32_e32 v4, vcc, 0x5800000, v4
	s_nop 1
	v_addc_co_u32_e32 v5, vcc, 0, v5, vcc
	global_store_dwordx4 v[4:5], v[0:3], off offset:1024
	s_waitcnt vmcnt(2)
	s_andn2_b64 vcc, exec, s[40:41]
	s_cbranch_vccnz .LBB0_701
	s_branch .LBB0_701

.LBB0_822:
	v_mov_b32_e32 v233, v244
	s_mov_b64 s[26:27], s[0:1]
	s_mov_b64 s[68:69], s[100:101]
	s_load_dwordx2 s[72:73], s[26:27], 0x0
	s_nop 0
	s_load_dwordx2 s[26:27], s[26:27], 0x20
	s_ashr_i32 s92, s4, 3
	s_ashr_i32 s93, s92, 31
	s_lshl_b64 s[70:71], s[92:93], 22
	s_waitcnt lgkmcnt(0)
	s_add_u32 s70, s68, s70
	s_addc_u32 s71, s69, s71
	s_add_u32 s5, s68, 0x100000
	s_mulk_i32 s92, 0xc00
	s_addc_u32 s61, s69, 0
	s_lshl_b32 s77, s90, 8
	s_ashr_i32 s93, s92, 31
	s_or_b32 s77, s77, s80
	v_ashrrev_i32_e32 v104, 1, v233
	s_lshl_b64 s[94:95], s[92:93], 2
	v_and_b32_e32 v104, -8, v104
	s_add_u32 s94, s5, s94
	v_add_u32_e32 v144, s77, v104
	s_addc_u32 s95, s61, s95
	s_addk_i32 s92, 0x6c00
	s_ashr_i32 s93, s92, 31
	v_ashrrev_i32_e32 v145, 31, v144
	s_lshl_b64 s[92:93], s[92:93], 2
	v_lshlrev_b64 v[146:147], 2, v[144:145]
	s_add_u32 s92, s5, s92
	v_lshl_add_u64 v[104:105], s[94:95], 0, v[146:147]
	s_movk_i32 s5, 0x2000
	v_lshl_add_u64 v[156:157], v[104:105], 0, s[12:13]
	v_add_co_u32_e32 v104, vcc, s5, v104
	v_lshl_add_u64 v[128:129], s[26:27], 0, v[146:147]
	s_nop 0
	v_addc_co_u32_e32 v105, vcc, 0, v105, vcc
	s_addc_u32 s93, s61, s93
	s_ashr_i32 s5, s4, 31
	s_lshl_b64 s[4:5], s[4:5], 8
	s_add_u32 s4, s4, s79
	s_addc_u32 s5, s5, 0
	v_and_or_b32 v224, v233, 15, s4
	v_mov_b32_e32 v225, s5
	s_mov_b32 s4, 0x10000
	v_lshl_add_u64 v[144:145], v[144:145], 1, s[70:71]
	v_lshl_add_u64 v[220:221], v[144:145], 0, s[34:35]
	s_lshl_b32 s26, s90, 2
	s_ashr_i32 s27, s26, 31
	s_lshl_b64 s[26:27], s[26:27], 2
	s_add_u32 s26, s68, s26
	s_addc_u32 s27, s69, s27
	s_add_u32 s26, s26, s87
	s_addc_u32 s27, s27, 0
	s_add_u32 s68, s26, 0x1700000
	s_addc_u32 s69, s27, 0
	v_lshlrev_b64 v[148:149], 12, v[224:225]
	v_lshl_add_u64 v[148:149], s[72:73], 0, v[148:149]
	v_lshl_add_u64 v[222:223], v[148:149], 0, v[146:147]
	v_lshl_add_u64 v[240:241], v[222:223], 0, s[16:17]
	global_load_dwordx4 v[184:187], v[222:223], off offset:16 nt
	global_load_dwordx4 v[188:191], v[222:223], off nt
	global_load_dwordx4 v[176:179], v[222:223], off offset:528 nt
	global_load_dwordx4 v[180:183], v[222:223], off offset:512 nt
	v_add_co_u32_e32 v148, vcc, s4, v222
	v_lshl_add_u64 v[144:145], v[222:223], 0, s[36:37]
	s_nop 0
	v_addc_co_u32_e32 v149, vcc, 0, v223, vcc
	global_load_dwordx4 v[172:175], v[148:149], off nt
	global_load_dwordx4 v[168:171], v[240:241], off offset:16 nt
	v_lshl_add_u64 v[240:241], v[222:223], 0, s[18:19]
	global_load_dwordx4 v[164:167], v[148:149], off offset:512 nt
	global_load_dwordx4 v[192:195], v[240:241], off offset:16 nt
	v_add_co_u32_e32 v240, vcc, s88, v222
	s_nop 1
	v_addc_co_u32_e32 v241, vcc, 0, v223, vcc
	global_load_dwordx4 v[196:199], v[240:241], off nt
	global_load_dwordx4 v[200:203], v[144:145], off offset:16 nt
	v_lshl_add_u64 v[144:145], v[222:223], 0, s[38:39]
	global_load_dwordx4 v[228:231], v[240:241], off offset:512 nt
	s_nop 0
	global_load_dwordx4 v[236:239], v[144:145], off offset:16 nt
	v_lshl_add_u64 v[158:159], v[128:129], 0, s[14:15]
	v_add_co_u32_e32 v128, vcc, s85, v128
	v_lshl_add_u64 v[148:149], s[92:93], 0, v[146:147]
	s_nop 0
	v_addc_co_u32_e32 v129, vcc, 0, v129, vcc
	v_lshl_add_u64 v[160:161], v[148:149], 0, s[14:15]
	v_add_co_u32_e32 v148, vcc, s85, v148
	global_load_dwordx4 v[108:111], v[104:105], off
	s_nop 0
	global_load_dwordx4 v[104:107], v[156:157], off offset:16
	v_addc_co_u32_e32 v149, vcc, 0, v149, vcc
	global_load_dwordx4 v[128:131], v[128:129], off
	s_nop 0
	global_load_dwordx4 v[132:135], v[158:159], off offset:16
	s_nop 0
	global_load_dwordx4 v[148:151], v[148:149], off
	s_nop 0
	global_load_dwordx4 v[152:155], v[160:161], off offset:16
	s_waitcnt vmcnt(0)
	v_pk_add_f32 v[148:149], v[148:149], 1.0 op_sel_hi:[1,0]
	s_nop 0
	v_pk_mul_f32 v[128:129], v[128:129], v[148:149]
	v_pk_add_f32 v[150:151], v[150:151], 1.0 op_sel_hi:[1,0]
	v_cmp_nlt_f32_e64 vcc, |v128|, s86
	v_pk_mul_f32 v[130:131], v[130:131], v[150:151]
	s_nop 0
	v_cndmask_b32_e32 v204, v232, v128, vcc
	v_cmp_nlt_f32_e64 vcc, |v129|, s86
	s_nop 1
	v_cndmask_b32_e32 v205, v232, v129, vcc
	v_cmp_nlt_f32_e64 vcc, |v130|, s86
	v_pk_add_f32 v[128:129], v[154:155], 1.0 op_sel_hi:[1,0]
	s_nop 0
	v_cndmask_b32_e32 v206, v232, v130, vcc
	v_cmp_nlt_f32_e64 vcc, |v131|, s86
	v_pk_mul_f32 v[128:129], v[134:135], v[128:129]
	s_nop 0
	v_cndmask_b32_e32 v207, v232, v131, vcc
	v_pk_add_f32 v[130:131], v[152:153], 1.0 op_sel_hi:[1,0]
	s_nop 0
	v_pk_mul_f32 v[130:131], v[132:133], v[130:131]
	s_nop 0
	v_cmp_nlt_f32_e64 vcc, |v130|, s86
	s_nop 1
	v_cndmask_b32_e32 v208, v232, v130, vcc
	v_cmp_nlt_f32_e64 vcc, |v131|, s86
	s_nop 1
	v_cndmask_b32_e32 v209, v232, v131, vcc
	v_cmp_nlt_f32_e64 vcc, |v128|, s86
	s_nop 1
	v_cndmask_b32_e32 v210, v232, v128, vcc
	v_cmp_nlt_f32_e64 vcc, |v129|, s86
	s_nop 1
	v_cndmask_b32_e32 v211, v232, v129, vcc
	global_load_dwordx4 v[128:131], v[156:157], off offset:528
	global_load_dwordx4 v[132:135], v[156:157], off offset:512
	global_load_dwordx4 v[148:151], v[158:159], off offset:528
	global_load_dwordx4 v[152:155], v[158:159], off offset:512
	s_nop 0
	global_load_dwordx4 v[156:159], v[160:161], off offset:528
	s_nop 0
	global_load_dwordx4 v[160:163], v[160:161], off offset:512
	s_waitcnt vmcnt(0)
	v_pk_add_f32 v[160:161], v[160:161], 1.0 op_sel_hi:[1,0]
	s_nop 0
	v_pk_mul_f32 v[152:153], v[152:153], v[160:161]
	v_pk_add_f32 v[162:163], v[162:163], 1.0 op_sel_hi:[1,0]
	v_cmp_nlt_f32_e64 vcc, |v152|, s86
	v_pk_mul_f32 v[154:155], v[154:155], v[162:163]
	s_nop 0
	v_cndmask_b32_e32 v212, v232, v152, vcc
	v_cmp_nlt_f32_e64 vcc, |v153|, s86
	s_nop 1
	v_cndmask_b32_e32 v213, v232, v153, vcc
	v_cmp_nlt_f32_e64 vcc, |v154|, s86
	v_pk_add_f32 v[152:153], v[158:159], 1.0 op_sel_hi:[1,0]
	s_nop 0
	v_cndmask_b32_e32 v218, v232, v154, vcc
	v_cmp_nlt_f32_e64 vcc, |v155|, s86
	v_pk_mul_f32 v[150:151], v[150:151], v[152:153]
	s_nop 0
	v_cndmask_b32_e32 v219, v232, v155, vcc
	v_pk_add_f32 v[154:155], v[156:157], 1.0 op_sel_hi:[1,0]
	s_nop 0
	v_pk_mul_f32 v[148:149], v[148:149], v[154:155]
	s_nop 0
	v_cmp_nlt_f32_e64 vcc, |v148|, s86
	s_nop 1
	v_cndmask_b32_e32 v214, v232, v148, vcc
	v_cmp_nlt_f32_e64 vcc, |v149|, s86
	s_nop 1
	v_cndmask_b32_e32 v215, v232, v149, vcc
	v_cmp_nlt_f32_e64 vcc, |v150|, s86
	s_nop 1
	v_cndmask_b32_e32 v216, v232, v150, vcc
	v_cmp_nlt_f32_e64 vcc, |v151|, s86
	s_nop 1
	v_cndmask_b32_e32 v217, v232, v151, vcc
	v_cmp_gt_u32_e64 s[4:5], 16, v233
	s_waitcnt vmcnt(10)
	v_pk_fma_f32 v[142:143], v[142:143], v[110:111], v[190:191]
	v_pk_fma_f32 v[140:141], v[140:141], v[108:109], v[188:189]
	v_pk_fma_f32 v[136:137], v[136:137], v[104:105], v[184:185]
	v_mul_f32_e32 v184, v141, v141
	v_mul_f32_e32 v185, v143, v143
	v_fmac_f32_e32 v184, v140, v140
	v_fmac_f32_e32 v185, v142, v142
	v_add_f32_e32 v184, v184, v185
	v_mul_f32_e32 v185, v137, v137
	v_pk_fma_f32 v[138:139], v[138:139], v[106:107], v[186:187]
	v_fmac_f32_e32 v185, v136, v136
	v_add_f32_e32 v184, v184, v185
	v_mul_f32_e32 v185, v139, v139
	v_fmac_f32_e32 v185, v138, v138
	v_lshlrev_b64 v[234:235], 11, v[224:225]
	v_add_f32_e32 v186, v185, v184
	v_pk_mul_f32 v[142:143], v[206:207], v[142:143]
	v_pk_mul_f32 v[140:141], v[204:205], v[140:141]
	v_pk_mul_f32 v[184:185], v[210:211], v[138:139]
	v_pk_mul_f32 v[138:139], v[208:209], v[136:137]
	v_lshl_add_u64 v[234:235], v[220:221], 0, v[234:235]
	v_cvt_pk_bf16_f32 v136, v140, v141
	v_cvt_pk_bf16_f32 v137, v142, v143
	v_cvt_pk_bf16_f32 v138, v138, v139
	v_cvt_pk_bf16_f32 v139, v184, v185
	s_waitcnt vmcnt(8)
	v_pk_fma_f32 v[126:127], v[126:127], v[134:135], v[182:183]
	v_pk_fma_f32 v[124:125], v[124:125], v[132:133], v[180:181]
	global_store_dwordx4 v[234:235], v[136:139], off
	v_pk_fma_f32 v[120:121], v[120:121], v[128:129], v[176:177]
	v_pk_fma_f32 v[122:123], v[122:123], v[130:131], v[178:179]
	v_mul_f32_e32 v136, v125, v125
	v_mul_f32_e32 v137, v127, v127
	v_fmac_f32_e32 v136, v124, v124
	v_fmac_f32_e32 v137, v126, v126
	v_add_f32_e32 v136, v136, v137
	v_mul_f32_e32 v137, v121, v121
	v_fmac_f32_e32 v137, v120, v120
	v_add_f32_e32 v136, v136, v137
	v_mul_f32_e32 v137, v123, v123
	v_fmac_f32_e32 v137, v122, v122
	v_add_f32_e32 v136, v137, v136
	v_add_f32_e32 v140, v186, v136
	ds_bpermute_b32 v141, v226, v140
	v_pk_mul_f32 v[138:139], v[120:121], v[214:215]
	v_pk_mul_f32 v[126:127], v[126:127], v[218:219]
	v_pk_mul_f32 v[124:125], v[124:125], v[212:213]
	v_pk_mul_f32 v[136:137], v[122:123], v[216:217]
	s_waitcnt lgkmcnt(0)
	v_add_f32_e32 v120, v140, v141
	ds_bpermute_b32 v121, v227, v120
	v_cvt_pk_bf16_f32 v122, v124, v125
	v_cvt_pk_bf16_f32 v123, v126, v127
	v_cvt_pk_bf16_f32 v124, v138, v139
	v_cvt_pk_bf16_f32 v125, v136, v137
	global_store_dwordx4 v[234:235], v[122:125], off offset:256
	s_and_saveexec_b64 s[70:71], s[4:5]
	s_cbranch_execz .LBB0_824
	v_lshlrev_b64 v[122:123], 6, v[224:225]
	v_lshl_add_u64 v[122:123], s[68:69], 0, v[122:123]
	s_waitcnt lgkmcnt(0)
	v_add_f32_e32 v120, v120, v121
	global_store_dword v[122:123], v120, off
